# v2 + leader buffer_wbl2 removed in the 8 seams whose phase stores are all sc1 write-through
# speedup vs baseline: 1.0010x; 1.0010x over previous
.LBB0_388:
	s_andn2_saveexec_b64 s[12:13], s[12:13]
	s_cbranch_execz .LBB0_408
	s_mov_b64 s[12:13], exec
	buffer_inv sc1
	s_waitcnt lgkmcnt(0)
	s_waitcnt vmcnt(0)
	v_mbcnt_lo_u32_b32 v1, s12, 0
	v_mbcnt_hi_u32_b32 v1, s13, v1
	v_cmp_eq_u32_e32 vcc, 0, v1
	s_and_saveexec_b64 s[14:15], vcc
	s_cbranch_execz .LBB0_391
	s_bcnt1_i32_b64 s3, s[12:13]
	v_mov_b32_e32 v2, 0x3000
	v_mov_b32_e32 v3, s3
	global_atomic_add v2, v2, v3, s[42:43] offset:1280 sc0

.LBB0_1467:
	s_andn2_saveexec_b64 s[10:11], s[10:11]
	s_cbranch_execz .LBB0_1487
	s_mov_b64 s[10:11], exec
	buffer_inv sc1
	s_waitcnt lgkmcnt(0)
	s_waitcnt vmcnt(0)
	v_mbcnt_lo_u32_b32 v1, s10, 0
	v_mbcnt_hi_u32_b32 v1, s11, v1
	v_cmp_eq_u32_e32 vcc, 0, v1
	s_and_saveexec_b64 s[12:13], vcc
	s_cbranch_execz .LBB0_1470
	s_bcnt1_i32_b64 s3, s[10:11]
	v_mov_b32_e32 v2, 0x3000
	v_mov_b32_e32 v3, s3
	global_atomic_add v2, v2, v3, s[42:43] offset:1280 sc0
